# scan I2: prioritised waves skip the generic dispatch chain (wave 4 straight to the solve, waves 6,7 to S1); solve: redundant zero pre-initialisation of 16 full-mask DPP broadcasts removed
# baseline (speedup 1.0000x reference)
; __device__ __forceinline__ void scan_phase(PREF p, char* smem, const int wid_u) {
;     ...
;       lds_barrier();
;       if (wave == 4) {
;         const int irow = lane >> 1, hb = lane & 1, blk = lane >> 5, il = irow & 15;
;         float x[8];
; #pragma unroll
;         for (int i = 0; i < 8; ++i) x[i] = (hb * 8 + i == il) ? 1.f : 0.f;
;         const float* nb = Nab + (blk * 16) * 32 + blk * 16 + hb * 8;
;         solve16<0>(x, nb);
; #pragma unroll
;         for (int i = 0; i < 8; ++i) TT[(blk * 16 + hb * 8 + i) * 40 + blk * 16 + il] = (bf16_t)(cvt_pk_bf16(x[i], 0.f) & 0xffff);
;         if (blk == 0) *(uint4*)(T11b + il * 40 + hb * 8) = pack8(x);
;         __builtin_amdgcn_wave_barrier();
;         const f32x4 zero = {0.f, 0.f, 0.f, 0.f};
;         bf16x8 zf;
; #pragma unroll
;         for (int i = 0; i < 8; ++i) zf[i] = 0;
;         bf16x8 n12 = zf, t22 = zf, t11 = zf;
;         if (fq < 2) {
;           float o[8];
;           const f32x4 n0 = *(const f32x4*)(Nab + fr * 32 + 16 + fq * 8), n1 = *(const f32x4*)(Nab + fr * 32 + 16 + fq * 8 + 4);
;           o[0] = n0[0]; o[1] = n0[1]; o[2] = n0[2]; o[3] = n0[3]; o[4] = n1[0]; o[5] = n1[1]; o[6] = n1[2]; o[7] = n1[3];
;           uint4 u = pack8(o);
;           n12 = *reinterpret_cast<bf16x8*>(&u);
;           t22 = *reinterpret_cast<const bf16x8*>(TT + (16 + fr) * 40 + 16 + fq * 8);
;           t11 = *reinterpret_cast<const bf16x8*>(T11b + fr * 40 + fq * 8);
;         }
;         const f32x4 m1 = MFMA16(n12, t22, zero);
;         *(uint2*)(M1T + fr * 40 + fq * 4) = pack4(m1);
;         __builtin_amdgcn_wave_barrier();
;         bf16x8 m1f = zf;
;         if (fq < 2) m1f = *reinterpret_cast<const bf16x8*>(M1T + fr * 40 + fq * 8);
;         const f32x4 t12 = MFMA16(t11, m1f, zero);
;         *(uint2*)(TT + (16 + fr) * 40 + fq * 4) = pack4(t12);
;       } else if (wave == 5) {
;         unsigned z0;
;         asm volatile("v_mov_b32 %0, 0" : "=v"(z0));
;         *(uint2*)(TT + (lane >> 2) * 40 + 16 + (lane & 3) * 4) = make_uint2(z0, z0);
;       } else if (wave == 2 || wave == 3 || wave >= 6) {
;         const int vtile = wave < 4 ? wave - 2 : wave - 4;
;         const bf16x8 vf = ldfrag(VT, 40, vtile * 16, 0, fr, fq);
;         const f32x4 zero = {0.f, 0.f, 0.f, 0.f};
; #pragma unroll
;         for (int tt = 0; tt < 2; ++tt) {
;           const f32x4 acc = MFMA16(ldfrag(NakT, 40, tt * 16, 0, fr, fq), vf, zero);
.LBB0_548:
	s_waitcnt lgkmcnt(0)
	s_barrier
	s_cmp_lt_u32 s90, 4
	s_cbranch_scc1 .Lprio_i2_skip
	s_cmp_eq_u32 s90, 5
	s_cbranch_scc1 .Lprio_i2_skip
	s_setprio 3
	s_cmp_eq_u32 s90, 4
	s_cbranch_scc1 .LBB0_559
	s_branch .LBB0_566

; template <int S0> __device__ __forceinline__ void solve16(float (&x)[8], const float* nb) {
;   if constexpr (S0 < 16) {
;     const float xs = (S0 >> 3) ? dpp_f<0xF5>(x[S0 & 7]) : dpp_f<0xA0>(x[S0 & 7]);
;     const f32x4 n0 = *(const f32x4*)(nb + S0 * 32), n1 = *(const f32x4*)(nb + S0 * 32 + 4);
;     x[0] += xs * n0[0]; x[1] += xs * n0[1]; x[2] += xs * n0[2]; x[3] += xs * n0[3];
;     x[4] += xs * n1[0]; x[5] += xs * n1[1]; x[6] += xs * n1[2]; x[7] += xs * n1[3];
;     if constexpr ((S0 & 3) == 3) __builtin_amdgcn_sched_barrier(0);
;     solve16<S0 + 1>(x, nb);
;   }
; }
; __device__ __forceinline__ void scan_phase(PREF p, char* smem, const int wid_u) {
;     ...
;         const int irow = lane >> 1, hb = lane & 1, blk = lane >> 5, il = irow & 15;
;         float x[8];
; #pragma unroll
;         for (int i = 0; i < 8; ++i) x[i] = (hb * 8 + i == il) ? 1.f : 0.f;
;         const float* nb = Nab + (blk * 16) * 32 + blk * 16 + hb * 8;
;         solve16<0>(x, nb);
; #pragma unroll
;         for (int i = 0; i < 8; ++i) TT[(blk * 16 + hb * 8 + i) * 40 + blk * 16 + il] = (bf16_t)(cvt_pk_bf16(x[i], 0.f) & 0xffff);
.LBB0_559:
	ds_read_b128 v[56:59], v166
	ds_read_b128 v[60:63], v166 offset:16
	ds_read_b128 v[64:67], v166 offset:128
	ds_read_b128 v[68:71], v166 offset:144
	ds_read_b128 v[94:97], v166 offset:256
	ds_read_b128 v[98:101], v166 offset:272
	ds_read_b128 v[102:105], v166 offset:384
	ds_read_b128 v[106:109], v166 offset:400
	s_nop 1
	v_mov_b32_dpp v78, v84 quad_perm:[0,0,2,2] row_mask:0xf bank_mask:0xf
	s_waitcnt lgkmcnt(7)
	v_pk_fma_f32 v[56:57], v[56:57], v[78:79], v[84:85] op_sel_hi:[1,0,1]
	v_pk_fma_f32 v[58:59], v[58:59], v[78:79], v[86:87] op_sel_hi:[1,0,1]
	s_waitcnt lgkmcnt(6)
	v_pk_fma_f32 v[60:61], v[60:61], v[78:79], v[88:89] op_sel_hi:[1,0,1]
	v_mov_b32_dpp v198, v57 quad_perm:[0,0,2,2] row_mask:0xf bank_mask:0xf
	s_waitcnt lgkmcnt(5)
	v_pk_fma_f32 v[56:57], v[64:65], v[198:199], v[56:57] op_sel_hi:[1,0,1]
	v_pk_fma_f32 v[58:59], v[66:67], v[198:199], v[58:59] op_sel_hi:[1,0,1]
	ds_read_b128 v[190:193], v166 offset:512
	ds_read_b128 v[194:197], v166 offset:528
	v_mov_b32_dpp v64, v58 quad_perm:[0,0,2,2] row_mask:0xf bank_mask:0xf
	s_waitcnt lgkmcnt(5)
	v_pk_fma_f32 v[58:59], v[96:97], v[64:65], v[58:59] op_sel_hi:[1,0,1]
	v_pk_fma_f32 v[60:61], v[68:69], v[198:199], v[60:61] op_sel_hi:[1,0,1]
	v_pk_fma_f32 v[56:57], v[94:95], v[64:65], v[56:57] op_sel_hi:[1,0,1]
	v_mov_b32_dpp v200, v59 quad_perm:[0,0,2,2] row_mask:0xf bank_mask:0xf
	s_waitcnt lgkmcnt(4)
	v_pk_fma_f32 v[60:61], v[98:99], v[64:65], v[60:61] op_sel_hi:[1,0,1]
	s_waitcnt lgkmcnt(3)
	v_pk_fma_f32 v[56:57], v[102:103], v[200:201], v[56:57] op_sel_hi:[1,0,1]
	s_waitcnt lgkmcnt(2)
	v_pk_fma_f32 v[60:61], v[106:107], v[200:201], v[60:61] op_sel_hi:[1,0,1]
	v_pk_fma_f32 v[58:59], v[104:105], v[200:201], v[58:59] op_sel_hi:[1,0,1]
	s_nop 0
	v_mov_b32_dpp v102, v60 quad_perm:[0,0,2,2] row_mask:0xf bank_mask:0xf
	s_waitcnt lgkmcnt(1)
	v_pk_fma_f32 v[246:247], v[190:191], v[102:103], v[56:57] op_sel_hi:[1,0,1]
	v_pk_fma_f32 v[56:57], v[62:63], v[78:79], v[90:91] op_sel_hi:[1,0,1]
	v_pk_fma_f32 v[248:249], v[192:193], v[102:103], v[58:59] op_sel_hi:[1,0,1]
	v_pk_fma_f32 v[56:57], v[70:71], v[198:199], v[56:57] op_sel_hi:[1,0,1]
	s_waitcnt lgkmcnt(0)
	v_pk_fma_f32 v[250:251], v[194:195], v[102:103], v[60:61] op_sel_hi:[1,0,1]
	v_pk_fma_f32 v[104:105], v[100:101], v[64:65], v[56:57] op_sel_hi:[1,0,1]
	ds_read_b128 v[56:59], v166 offset:640
	ds_read_b128 v[60:63], v166 offset:656
	ds_read_b128 v[64:67], v166 offset:768
	ds_read_b128 v[68:71], v166 offset:784
	ds_read_b128 v[94:97], v166 offset:896
	ds_read_b128 v[98:101], v166 offset:912
	v_pk_fma_f32 v[104:105], v[108:109], v[200:201], v[104:105] op_sel_hi:[1,0,1]
	v_pk_fma_f32 v[252:253], v[196:197], v[102:103], v[104:105] op_sel_hi:[1,0,1]
	s_nop 0
	v_mov_b32_dpp v78, v251 quad_perm:[0,0,2,2] row_mask:0xf bank_mask:0xf
	ds_read_b128 v[102:105], v166 offset:1024
	ds_read_b128 v[106:109], v166 offset:1040
	ds_read_b128 v[190:193], v166 offset:1152
	ds_read_b128 v[194:197], v166 offset:1168
	ds_read_b128 v[198:201], v166 offset:1280
	ds_read_b128 v[202:205], v166 offset:1296
	ds_read_b128 v[206:209], v166 offset:1408
	ds_read_b128 v[210:213], v166 offset:1424
	s_waitcnt lgkmcnt(12)
	v_pk_fma_f32 v[62:63], v[62:63], v[78:79], v[252:253] op_sel_hi:[1,0,1]
	v_pk_fma_f32 v[56:57], v[56:57], v[78:79], v[246:247] op_sel_hi:[1,0,1]
	v_pk_fma_f32 v[58:59], v[58:59], v[78:79], v[248:249] op_sel_hi:[1,0,1]
	v_mov_b32_dpp v252, v62 quad_perm:[0,0,2,2] row_mask:0xf bank_mask:0xf
	s_waitcnt lgkmcnt(10)
	v_pk_fma_f32 v[62:63], v[70:71], v[252:253], v[62:63] op_sel_hi:[1,0,1]
	v_pk_fma_f32 v[56:57], v[64:65], v[252:253], v[56:57] op_sel_hi:[1,0,1]
	s_nop 0
	v_mov_b32_dpp v70, v63 quad_perm:[0,0,2,2] row_mask:0xf bank_mask:0xf
	s_waitcnt lgkmcnt(9)
	v_pk_fma_f32 v[56:57], v[94:95], v[70:71], v[56:57] op_sel_hi:[1,0,1]
	v_pk_fma_f32 v[60:61], v[60:61], v[78:79], v[250:251] op_sel_hi:[1,0,1]
	v_pk_fma_f32 v[58:59], v[66:67], v[252:253], v[58:59] op_sel_hi:[1,0,1]
	v_mov_b32_dpp v64, v56 quad_perm:[1,1,3,3] row_mask:0xf bank_mask:0xf
	v_pk_fma_f32 v[60:61], v[68:69], v[252:253], v[60:61] op_sel_hi:[1,0,1]
	v_pk_fma_f32 v[58:59], v[96:97], v[70:71], v[58:59] op_sel_hi:[1,0,1]
	s_waitcnt lgkmcnt(7)
	v_pk_fma_f32 v[56:57], v[102:103], v[64:65], v[56:57] op_sel_hi:[1,0,1]
	v_pk_fma_f32 v[62:63], v[100:101], v[70:71], v[62:63] op_sel_hi:[1,0,1]
	v_pk_fma_f32 v[60:61], v[98:99], v[70:71], v[60:61] op_sel_hi:[1,0,1]
	v_mov_b32_dpp v66, v57 quad_perm:[1,1,3,3] row_mask:0xf bank_mask:0xf
	v_pk_fma_f32 v[58:59], v[104:105], v[64:65], v[58:59] op_sel_hi:[1,0,1]
	s_waitcnt lgkmcnt(6)
	v_pk_fma_f32 v[62:63], v[108:109], v[64:65], v[62:63] op_sel_hi:[1,0,1]
	v_pk_fma_f32 v[60:61], v[106:107], v[64:65], v[60:61] op_sel_hi:[1,0,1]
	s_waitcnt lgkmcnt(5)
; template <int S0> __device__ __forceinline__ void solve16(float (&x)[8], const float* nb) {
;   if constexpr (S0 < 16) {
;     const float xs = (S0 >> 3) ? dpp_f<0xF5>(x[S0 & 7]) : dpp_f<0xA0>(x[S0 & 7]);
;     const f32x4 n0 = *(const f32x4*)(nb + S0 * 32), n1 = *(const f32x4*)(nb + S0 * 32 + 4);
;     x[0] += xs * n0[0]; x[1] += xs * n0[1]; x[2] += xs * n0[2]; x[3] += xs * n0[3];
;     x[4] += xs * n1[0]; x[5] += xs * n1[1]; x[6] += xs * n1[2]; x[7] += xs * n1[3];
;     if constexpr ((S0 & 3) == 3) __builtin_amdgcn_sched_barrier(0);
;     solve16<S0 + 1>(x, nb);
;   }
; }
; __device__ __forceinline__ void scan_phase(PREF p, char* smem, const int wid_u) {
;     ...
;         const int irow = lane >> 1, hb = lane & 1, blk = lane >> 5, il = irow & 15;
;         float x[8];
; #pragma unroll
;         for (int i = 0; i < 8; ++i) x[i] = (hb * 8 + i == il) ? 1.f : 0.f;
;         const float* nb = Nab + (blk * 16) * 32 + blk * 16 + hb * 8;
;         solve16<0>(x, nb);
; #pragma unroll
;         for (int i = 0; i < 8; ++i) TT[(blk * 16 + hb * 8 + i) * 40 + blk * 16 + il] = (bf16_t)(cvt_pk_bf16(x[i], 0.f) & 0xffff);
;         if (blk == 0) *(uint4*)(T11b + il * 40 + hb * 8) = pack8(x);
;         __builtin_amdgcn_wave_barrier();
;         const f32x4 zero = {0.f, 0.f, 0.f, 0.f};
;         bf16x8 zf;
; #pragma unroll
;         for (int i = 0; i < 8; ++i) zf[i] = 0;
;         bf16x8 n12 = zf, t22 = zf, t11 = zf;
;         if (fq < 2) {
;           float o[8];
;           const f32x4 n0 = *(const f32x4*)(Nab + fr * 32 + 16 + fq * 8), n1 = *(const f32x4*)(Nab + fr * 32 + 16 + fq * 8 + 4);
;           o[0] = n0[0]; o[1] = n0[1]; o[2] = n0[2]; o[3] = n0[3]; o[4] = n1[0]; o[5] = n1[1]; o[6] = n1[2]; o[7] = n1[3];
;           uint4 u = pack8(o);
;           n12 = *reinterpret_cast<bf16x8*>(&u);
;           t22 = *reinterpret_cast<const bf16x8*>(TT + (16 + fr) * 40 + 16 + fq * 8);
;           t11 = *reinterpret_cast<const bf16x8*>(T11b + fr * 40 + fq * 8);
;         }
	v_pk_fma_f32 v[58:59], v[192:193], v[66:67], v[58:59] op_sel_hi:[1,0,1]
	v_pk_fma_f32 v[56:57], v[190:191], v[66:67], v[56:57] op_sel_hi:[1,0,1]
	s_waitcnt lgkmcnt(4)
	v_pk_fma_f32 v[62:63], v[196:197], v[66:67], v[62:63] op_sel_hi:[1,0,1]
	v_mov_b32_dpp v64, v58 quad_perm:[1,1,3,3] row_mask:0xf bank_mask:0xf
	v_pk_fma_f32 v[60:61], v[194:195], v[66:67], v[60:61] op_sel_hi:[1,0,1]
	s_waitcnt lgkmcnt(3)
	v_pk_fma_f32 v[58:59], v[200:201], v[64:65], v[58:59] op_sel_hi:[1,0,1]
	s_waitcnt lgkmcnt(2)
	v_pk_fma_f32 v[60:61], v[202:203], v[64:65], v[60:61] op_sel_hi:[1,0,1]
	v_pk_fma_f32 v[56:57], v[198:199], v[64:65], v[56:57] op_sel_hi:[1,0,1]
	v_mov_b32_dpp v66, v59 quad_perm:[1,1,3,3] row_mask:0xf bank_mask:0xf
	v_pk_fma_f32 v[62:63], v[204:205], v[64:65], v[62:63] op_sel_hi:[1,0,1]
	s_waitcnt lgkmcnt(0)
	v_pk_fma_f32 v[60:61], v[210:211], v[66:67], v[60:61] op_sel_hi:[1,0,1]
	v_pk_fma_f32 v[56:57], v[206:207], v[66:67], v[56:57] op_sel_hi:[1,0,1]
	v_pk_fma_f32 v[58:59], v[208:209], v[66:67], v[58:59] op_sel_hi:[1,0,1]
	v_pk_fma_f32 v[62:63], v[212:213], v[66:67], v[62:63] op_sel_hi:[1,0,1]
	v_mov_b32_dpp v64, v60 quad_perm:[1,1,3,3] row_mask:0xf bank_mask:0xf
	ds_read_b128 v[214:217], v166 offset:1536
	ds_read_b128 v[218:221], v166 offset:1552
	ds_read_b128 v[222:225], v166 offset:1664
	ds_read_b128 v[226:229], v166 offset:1680
	ds_read_b128 v[230:233], v166 offset:1792
	ds_read_b128 v[234:237], v166 offset:1808
	ds_read_b128 v[238:241], v166 offset:1920
	ds_read_b128 v[242:245], v166 offset:1936
	s_waitcnt lgkmcnt(7)
	v_pk_fma_f32 v[56:57], v[214:215], v[64:65], v[56:57] op_sel_hi:[1,0,1]
	v_pk_fma_f32 v[58:59], v[216:217], v[64:65], v[58:59] op_sel_hi:[1,0,1]
	s_waitcnt lgkmcnt(6)
	v_pk_fma_f32 v[60:61], v[218:219], v[64:65], v[60:61] op_sel_hi:[1,0,1]
	v_pk_fma_f32 v[62:63], v[220:221], v[64:65], v[62:63] op_sel_hi:[1,0,1]
	s_nop 1
	v_mov_b32_dpp v64, v61 quad_perm:[1,1,3,3] row_mask:0xf bank_mask:0xf
	s_waitcnt lgkmcnt(5)
	v_pk_fma_f32 v[56:57], v[222:223], v[64:65], v[56:57] op_sel_hi:[1,0,1]
	v_pk_fma_f32 v[58:59], v[224:225], v[64:65], v[58:59] op_sel_hi:[1,0,1]
	s_waitcnt lgkmcnt(4)
	v_pk_fma_f32 v[60:61], v[226:227], v[64:65], v[60:61] op_sel_hi:[1,0,1]
	v_pk_fma_f32 v[62:63], v[228:229], v[64:65], v[62:63] op_sel_hi:[1,0,1]
	s_nop 1
	v_mov_b32_dpp v64, v62 quad_perm:[1,1,3,3] row_mask:0xf bank_mask:0xf
	s_waitcnt lgkmcnt(3)
	v_pk_fma_f32 v[56:57], v[230:231], v[64:65], v[56:57] op_sel_hi:[1,0,1]
	v_pk_fma_f32 v[58:59], v[232:233], v[64:65], v[58:59] op_sel_hi:[1,0,1]
	s_waitcnt lgkmcnt(2)
	v_pk_fma_f32 v[60:61], v[234:235], v[64:65], v[60:61] op_sel_hi:[1,0,1]
	v_pk_fma_f32 v[62:63], v[236:237], v[64:65], v[62:63] op_sel_hi:[1,0,1]
	s_nop 1
	v_mov_b32_dpp v64, v63 quad_perm:[1,1,3,3] row_mask:0xf bank_mask:0xf
	s_waitcnt lgkmcnt(1)
	v_pk_fma_f32 v[56:57], v[238:239], v[64:65], v[56:57] op_sel_hi:[1,0,1]
	v_pk_fma_f32 v[58:59], v[240:241], v[64:65], v[58:59] op_sel_hi:[1,0,1]
	s_waitcnt lgkmcnt(0)
	v_pk_fma_f32 v[60:61], v[242:243], v[64:65], v[60:61] op_sel_hi:[1,0,1]
	v_pk_fma_f32 v[62:63], v[244:245], v[64:65], v[62:63] op_sel_hi:[1,0,1]
	v_cvt_pk_bf16_f32 v64, v56, s0
	ds_write_b16 v174, v64 offset:13312
	v_cvt_pk_bf16_f32 v64, v57, s0
	ds_write_b16 v174, v64 offset:13392
	v_cvt_pk_bf16_f32 v64, v58, s0
	ds_write_b16 v174, v64 offset:13472
	v_cvt_pk_bf16_f32 v64, v59, s0
	ds_write_b16 v174, v64 offset:13552
	v_cvt_pk_bf16_f32 v64, v60, s0
	ds_write_b16 v174, v64 offset:13632
	v_cvt_pk_bf16_f32 v64, v61, s0
	ds_write_b16 v174, v64 offset:13712
	v_cvt_pk_bf16_f32 v64, v62, s0
	ds_write_b16 v174, v64 offset:13792
	v_cvt_pk_bf16_f32 v64, v63, s0
	ds_write_b16 v174, v64 offset:13872
	s_and_saveexec_b64 s[40:41], s[18:19]
	v_cvt_pk_bf16_f32 v56, v56, v57
	v_cvt_pk_bf16_f32 v57, v58, v59
	v_cvt_pk_bf16_f32 v58, v60, v61
	v_cvt_pk_bf16_f32 v59, v62, v63
	ds_write_b128 v167, v[56:59] offset:45056
	s_or_b64 exec, exec, s[40:41]
	v_mov_b32_e32 v56, 0
	v_mov_b32_e32 v60, 0
	v_mov_b32_e32 v61, 0
	v_mov_b32_e32 v62, 0
	v_mov_b32_e32 v63, 0
	v_mov_b32_e32 v64, 0
	v_mov_b32_e32 v65, 0
	v_mov_b32_e32 v66, 0
	v_mov_b32_e32 v67, 0
	v_mov_b32_e32 v68, 0
	v_mov_b32_e32 v69, 0
	v_mov_b32_e32 v70, 0
	v_mov_b32_e32 v71, 0
	s_and_saveexec_b64 s[40:41], s[18:19]
	s_cbranch_execz .LBB0_563
	ds_read_b128 v[68:71], v132 offset:64
	ds_read_b128 v[94:97], v132 offset:80
	ds_read_b128 v[64:67], v133 offset:14624
	ds_read_b128 v[60:63], v134 offset:45056
	s_waitcnt lgkmcnt(3)
	v_cvt_pk_bf16_f32 v68, v68, v69
	v_cvt_pk_bf16_f32 v69, v70, v71
	s_waitcnt lgkmcnt(2)
	v_cvt_pk_bf16_f32 v70, v94, v95
	v_cvt_pk_bf16_f32 v71, v96, v97
